# FFN-in SwiGLU epilogue regenerated: out = g*up / ((1+exp2(-log2e*rstd*g)) * (ms+eps)), 64 instead of 88 VALU slots per 8 outputs
# speedup vs baseline: 1.0150x; 1.0106x over previous
.LBB0_612:
	s_and_b64 vcc, exec, s[8:9]
	s_cbranch_vccz .LBB0_611
	v_lshlrev_b64 v[154:155], 6, v[150:151]
	v_lshl_add_u64 v[154:155], v[142:143], 0, v[154:155]
	v_add_co_u32_e32 v156, vcc, 0x2000, v154
	s_nop 1
	v_addc_co_u32_e32 v157, vcc, 0, v155, vcc
	global_load_dwordx4 v[170:173], v[154:155], off
	global_load_dwordx4 v[174:177], v[154:155], off offset:1024
	global_load_dwordx4 v[178:181], v[154:155], off offset:2048
	global_load_dwordx4 v[182:185], v[154:155], off offset:3072
	global_load_dwordx4 v[186:189], v[156:157], off
	global_load_dwordx4 v[200:203], v[156:157], off offset:1024
	global_load_dwordx4 v[204:207], v[156:157], off offset:2048
	global_load_dwordx4 v[208:211], v[156:157], off offset:3072
	v_or_b32_e32 v152, s91, v136
	v_lshl_or_b32 v152, s14, 7, v152
	v_ashrrev_i32_e32 v153, 31, v152
	v_mov_b64_e32 v[212:213], s[64:65]
	v_lshlrev_b64 v[214:215], 1, v[152:153]
	s_waitcnt vmcnt(0)
	v_add_f32_e32 v170, v171, v170
	v_add_f32_e32 v172, v172, v173
	v_add_f32_e32 v174, v175, v174
	v_add_f32_e32 v176, v176, v177
	v_add_f32_e32 v178, v179, v178
	v_add_f32_e32 v180, v180, v181
	v_add_f32_e32 v182, v183, v182
	v_add_f32_e32 v184, v184, v185
	v_add_f32_e32 v186, v187, v186
	v_add_f32_e32 v188, v188, v189
	v_add_f32_e32 v200, v201, v200
	v_add_f32_e32 v202, v202, v203
	v_add_f32_e32 v204, v205, v204
	v_add_f32_e32 v206, v206, v207
	v_add_f32_e32 v208, v209, v208
	v_add_f32_e32 v210, v210, v211
	v_add_f32_e32 v170, v170, v172
	v_add_f32_e32 v174, v174, v176
	v_add_f32_e32 v178, v178, v180
	v_add_f32_e32 v182, v182, v184
	v_add_f32_e32 v186, v186, v188
	v_add_f32_e32 v200, v200, v202
	v_add_f32_e32 v204, v204, v206
	v_add_f32_e32 v208, v208, v210
	ds_bpermute_b32 v171, v197, v170
	ds_bpermute_b32 v175, v197, v174
	ds_bpermute_b32 v179, v197, v178
	ds_bpermute_b32 v183, v197, v182
	ds_bpermute_b32 v187, v197, v186
	ds_bpermute_b32 v201, v197, v200
	ds_bpermute_b32 v205, v197, v204
	ds_bpermute_b32 v209, v197, v208
	s_waitcnt lgkmcnt(0)
	v_add_f32_e32 v170, v170, v171
	v_add_f32_e32 v174, v174, v175
	v_add_f32_e32 v178, v178, v179
	v_add_f32_e32 v182, v182, v183
	v_add_f32_e32 v186, v186, v187
	v_add_f32_e32 v200, v200, v201
	v_add_f32_e32 v204, v204, v205
	v_add_f32_e32 v208, v208, v209
	ds_bpermute_b32 v171, v198, v170
	ds_bpermute_b32 v175, v198, v174
	ds_bpermute_b32 v179, v198, v178
	ds_bpermute_b32 v183, v198, v182
	ds_bpermute_b32 v187, v198, v186
	ds_bpermute_b32 v201, v198, v200
	ds_bpermute_b32 v205, v198, v204
	ds_bpermute_b32 v209, v198, v208
	s_waitcnt lgkmcnt(0)
	v_add_f32_e32 v170, v170, v171
	v_add_f32_e32 v174, v174, v175
	v_add_f32_e32 v178, v178, v179
	v_add_f32_e32 v182, v182, v183
	v_add_f32_e32 v186, v186, v187
	v_add_f32_e32 v200, v200, v201
	v_add_f32_e32 v204, v204, v205
	v_add_f32_e32 v208, v208, v209
	v_fmamk_f32 v170, v170, 0x3a800000, v216
	v_fmamk_f32 v174, v174, 0x3a800000, v216
	v_fmamk_f32 v178, v178, 0x3a800000, v216
	v_fmamk_f32 v182, v182, 0x3a800000, v216
	v_fmamk_f32 v186, v186, 0x3a800000, v216
	v_fmamk_f32 v200, v200, 0x3a800000, v216
	v_fmamk_f32 v204, v204, 0x3a800000, v216
	v_fmamk_f32 v208, v208, 0x3a800000, v216
	v_mov_b32_e32 v172, v170
	v_mov_b32_e32 v176, v174
	v_mov_b32_e32 v180, v178
	v_mov_b32_e32 v184, v182
	v_mov_b32_e32 v188, v186
	v_mov_b32_e32 v202, v200
	v_mov_b32_e32 v206, v204
	v_mov_b32_e32 v210, v208
	v_cmp_gt_f32_e32 vcc, s29, v170
	v_mul_f32_e32 v171, 0x4b800000, v170
	s_nop 0
	v_cndmask_b32_e32 v170, v170, v171, vcc
	v_rsq_f32_e32 v170, v170
	s_nop 0
	v_mul_f32_e32 v171, 0x45800000, v170
	v_cndmask_b32_e32 v170, v170, v171, vcc
	v_cmp_gt_f32_e32 vcc, s29, v174
	v_mul_f32_e32 v175, 0x4b800000, v174
	s_nop 0
	v_cndmask_b32_e32 v174, v174, v175, vcc
	v_rsq_f32_e32 v174, v174
	s_nop 0
	v_mul_f32_e32 v175, 0x45800000, v174
	v_cndmask_b32_e32 v174, v174, v175, vcc
	v_cmp_gt_f32_e32 vcc, s29, v178
	v_mul_f32_e32 v179, 0x4b800000, v178
	s_nop 0
	v_cndmask_b32_e32 v178, v178, v179, vcc
	v_rsq_f32_e32 v178, v178
	s_nop 0
	v_mul_f32_e32 v179, 0x45800000, v178
	v_cndmask_b32_e32 v178, v178, v179, vcc
	v_cmp_gt_f32_e32 vcc, s29, v182
	v_mul_f32_e32 v183, 0x4b800000, v182
	s_nop 0
	v_cndmask_b32_e32 v182, v182, v183, vcc
	v_rsq_f32_e32 v182, v182
	s_nop 0
	v_mul_f32_e32 v183, 0x45800000, v182
	v_cndmask_b32_e32 v182, v182, v183, vcc
	v_cmp_gt_f32_e32 vcc, s29, v186
	v_mul_f32_e32 v187, 0x4b800000, v186
	s_nop 0
	v_cndmask_b32_e32 v186, v186, v187, vcc
	v_rsq_f32_e32 v186, v186
	s_nop 0
	v_mul_f32_e32 v187, 0x45800000, v186
	v_cndmask_b32_e32 v186, v186, v187, vcc
	v_cmp_gt_f32_e32 vcc, s29, v200
	v_mul_f32_e32 v201, 0x4b800000, v200
	s_nop 0
	v_cndmask_b32_e32 v200, v200, v201, vcc
	v_rsq_f32_e32 v200, v200
	s_nop 0
	v_mul_f32_e32 v201, 0x45800000, v200
	v_cndmask_b32_e32 v200, v200, v201, vcc
	v_cmp_gt_f32_e32 vcc, s29, v204
	v_mul_f32_e32 v205, 0x4b800000, v204
	s_nop 0
	v_cndmask_b32_e32 v204, v204, v205, vcc
	v_rsq_f32_e32 v204, v204
	s_nop 0
	v_mul_f32_e32 v205, 0x45800000, v204
	v_cndmask_b32_e32 v204, v204, v205, vcc
	v_cmp_gt_f32_e32 vcc, s29, v208
	v_mul_f32_e32 v209, 0x4b800000, v208
	s_nop 0
	v_cndmask_b32_e32 v208, v208, v209, vcc
	v_rsq_f32_e32 v208, v208
	s_nop 0
	v_mul_f32_e32 v209, 0x45800000, v208
	v_cndmask_b32_e32 v208, v208, v209, vcc
	v_mul_f32_e32 v238, 0xbfb8aa3b, v170
	v_pk_mul_f32 v[116:117], v[124:125], v[116:117]
	v_pk_mul_f32 v[118:119], v[126:127], v[118:119]
	v_pk_mul_f32 v[112:113], v[120:121], v[112:113]
	v_pk_mul_f32 v[114:115], v[122:123], v[114:115]
	v_mul_f32_e32 v124, v238, v124
	v_mul_f32_e32 v125, v238, v125
	v_mul_f32_e32 v126, v238, v126
	v_mul_f32_e32 v127, v238, v127
	v_mul_f32_e32 v120, v238, v120
	v_mul_f32_e32 v121, v238, v121
	v_mul_f32_e32 v122, v238, v122
	v_mul_f32_e32 v123, v238, v123
	v_exp_f32_e32 v124, v124
	v_exp_f32_e32 v125, v125
	v_exp_f32_e32 v126, v126
	v_exp_f32_e32 v127, v127
	v_exp_f32_e32 v120, v120
	v_exp_f32_e32 v121, v121
	v_exp_f32_e32 v122, v122
	v_exp_f32_e32 v123, v123
	v_fma_f32 v124, v124, v172, v172
	v_fma_f32 v125, v125, v172, v172
	v_fma_f32 v126, v126, v172, v172
	v_fma_f32 v127, v127, v172, v172
	v_fma_f32 v120, v120, v172, v172
	v_fma_f32 v121, v121, v172, v172
	v_fma_f32 v122, v122, v172, v172
	v_fma_f32 v123, v123, v172, v172
	v_rcp_f32_e32 v124, v124
	v_rcp_f32_e32 v125, v125
	v_rcp_f32_e32 v126, v126
	v_rcp_f32_e32 v127, v127
	v_rcp_f32_e32 v120, v120
	v_rcp_f32_e32 v121, v121
	v_rcp_f32_e32 v122, v122
	v_rcp_f32_e32 v123, v123
	v_add_u32_e32 v242, 0, v150
	v_mad_i64_i32 v[240:241], s[8:9], v242, s72, v[212:213]
	v_pk_mul_f32 v[116:117], v[116:117], v[124:125]
	v_pk_mul_f32 v[118:119], v[118:119], v[126:127]
	v_pk_mul_f32 v[112:113], v[112:113], v[120:121]
	v_pk_mul_f32 v[114:115], v[114:115], v[122:123]
	v_lshl_add_u64 v[240:241], v[240:241], 0, v[214:215]
	v_cvt_pk_bf16_f32 v244, v116, v117
	v_cvt_pk_bf16_f32 v245, v118, v119
	v_cvt_pk_bf16_f32 v246, v112, v113
	v_cvt_pk_bf16_f32 v247, v114, v115
	global_store_dwordx4 v[240:241], v[244:247], off sc1
	s_nop 1
	v_mul_f32_e32 v238, 0xbfb8aa3b, v174
	v_pk_mul_f32 v[100:101], v[108:109], v[100:101]
	v_pk_mul_f32 v[102:103], v[110:111], v[102:103]
	v_pk_mul_f32 v[96:97], v[104:105], v[96:97]
	v_pk_mul_f32 v[98:99], v[106:107], v[98:99]
	v_mul_f32_e32 v108, v238, v108
	v_mul_f32_e32 v109, v238, v109
	v_mul_f32_e32 v110, v238, v110
	v_mul_f32_e32 v111, v238, v111
	v_mul_f32_e32 v104, v238, v104
	v_mul_f32_e32 v105, v238, v105
	v_mul_f32_e32 v106, v238, v106
	v_mul_f32_e32 v107, v238, v107
	v_exp_f32_e32 v108, v108
	v_exp_f32_e32 v109, v109
	v_exp_f32_e32 v110, v110
	v_exp_f32_e32 v111, v111
	v_exp_f32_e32 v104, v104
	v_exp_f32_e32 v105, v105
	v_exp_f32_e32 v106, v106
	v_exp_f32_e32 v107, v107
	v_fma_f32 v108, v108, v176, v176
	v_fma_f32 v109, v109, v176, v176
	v_fma_f32 v110, v110, v176, v176
	v_fma_f32 v111, v111, v176, v176
	v_fma_f32 v104, v104, v176, v176
	v_fma_f32 v105, v105, v176, v176
	v_fma_f32 v106, v106, v176, v176
	v_fma_f32 v107, v107, v176, v176
	v_rcp_f32_e32 v108, v108
	v_rcp_f32_e32 v109, v109
	v_rcp_f32_e32 v110, v110
	v_rcp_f32_e32 v111, v111
	v_rcp_f32_e32 v104, v104
	v_rcp_f32_e32 v105, v105
	v_rcp_f32_e32 v106, v106
	v_rcp_f32_e32 v107, v107
	v_add_u32_e32 v242, 16, v150
	v_mad_i64_i32 v[240:241], s[8:9], v242, s72, v[212:213]
	v_pk_mul_f32 v[100:101], v[100:101], v[108:109]
	v_pk_mul_f32 v[102:103], v[102:103], v[110:111]
	v_pk_mul_f32 v[96:97], v[96:97], v[104:105]
	v_pk_mul_f32 v[98:99], v[98:99], v[106:107]
	v_lshl_add_u64 v[240:241], v[240:241], 0, v[214:215]
	v_cvt_pk_bf16_f32 v244, v100, v101
	v_cvt_pk_bf16_f32 v245, v102, v103
	v_cvt_pk_bf16_f32 v246, v96, v97
	v_cvt_pk_bf16_f32 v247, v98, v99
	global_store_dwordx4 v[240:241], v[244:247], off sc1
	s_nop 1
	v_mul_f32_e32 v238, 0xbfb8aa3b, v178
	v_pk_mul_f32 v[84:85], v[92:93], v[84:85]
	v_pk_mul_f32 v[86:87], v[94:95], v[86:87]
	v_pk_mul_f32 v[80:81], v[88:89], v[80:81]
	v_pk_mul_f32 v[82:83], v[90:91], v[82:83]
	v_mul_f32_e32 v92, v238, v92
	v_mul_f32_e32 v93, v238, v93
	v_mul_f32_e32 v94, v238, v94
	v_mul_f32_e32 v95, v238, v95
	v_mul_f32_e32 v88, v238, v88
	v_mul_f32_e32 v89, v238, v89
	v_mul_f32_e32 v90, v238, v90
	v_mul_f32_e32 v91, v238, v91
	v_exp_f32_e32 v92, v92
	v_exp_f32_e32 v93, v93
	v_exp_f32_e32 v94, v94
	v_exp_f32_e32 v95, v95
	v_exp_f32_e32 v88, v88
	v_exp_f32_e32 v89, v89
	v_exp_f32_e32 v90, v90
	v_exp_f32_e32 v91, v91
	v_fma_f32 v92, v92, v180, v180
	v_fma_f32 v93, v93, v180, v180
	v_fma_f32 v94, v94, v180, v180
	v_fma_f32 v95, v95, v180, v180
	v_fma_f32 v88, v88, v180, v180
	v_fma_f32 v89, v89, v180, v180
	v_fma_f32 v90, v90, v180, v180
	v_fma_f32 v91, v91, v180, v180
	v_rcp_f32_e32 v92, v92
	v_rcp_f32_e32 v93, v93
	v_rcp_f32_e32 v94, v94
	v_rcp_f32_e32 v95, v95
	v_rcp_f32_e32 v88, v88
	v_rcp_f32_e32 v89, v89
	v_rcp_f32_e32 v90, v90
	v_rcp_f32_e32 v91, v91
	v_add_u32_e32 v242, 32, v150
	v_mad_i64_i32 v[240:241], s[8:9], v242, s72, v[212:213]
	v_pk_mul_f32 v[84:85], v[84:85], v[92:93]
	v_pk_mul_f32 v[86:87], v[86:87], v[94:95]
	v_pk_mul_f32 v[80:81], v[80:81], v[88:89]
	v_pk_mul_f32 v[82:83], v[82:83], v[90:91]
	v_lshl_add_u64 v[240:241], v[240:241], 0, v[214:215]
	v_cvt_pk_bf16_f32 v244, v84, v85
	v_cvt_pk_bf16_f32 v245, v86, v87
	v_cvt_pk_bf16_f32 v246, v80, v81
	v_cvt_pk_bf16_f32 v247, v82, v83
	global_store_dwordx4 v[240:241], v[244:247], off sc1
	s_nop 1
	v_mul_f32_e32 v238, 0xbfb8aa3b, v182
	v_pk_mul_f32 v[68:69], v[76:77], v[68:69]
	v_pk_mul_f32 v[70:71], v[78:79], v[70:71]
	v_pk_mul_f32 v[64:65], v[72:73], v[64:65]
	v_pk_mul_f32 v[66:67], v[74:75], v[66:67]
	v_mul_f32_e32 v76, v238, v76
	v_mul_f32_e32 v77, v238, v77
	v_mul_f32_e32 v78, v238, v78
	v_mul_f32_e32 v79, v238, v79
	v_mul_f32_e32 v72, v238, v72
	v_mul_f32_e32 v73, v238, v73
	v_mul_f32_e32 v74, v238, v74
	v_mul_f32_e32 v75, v238, v75
	v_exp_f32_e32 v76, v76
	v_exp_f32_e32 v77, v77
	v_exp_f32_e32 v78, v78
	v_exp_f32_e32 v79, v79
	v_exp_f32_e32 v72, v72
	v_exp_f32_e32 v73, v73
	v_exp_f32_e32 v74, v74
	v_exp_f32_e32 v75, v75
	v_fma_f32 v76, v76, v184, v184
	v_fma_f32 v77, v77, v184, v184
	v_fma_f32 v78, v78, v184, v184
	v_fma_f32 v79, v79, v184, v184
	v_fma_f32 v72, v72, v184, v184
	v_fma_f32 v73, v73, v184, v184
	v_fma_f32 v74, v74, v184, v184
	v_fma_f32 v75, v75, v184, v184
	v_rcp_f32_e32 v76, v76
	v_rcp_f32_e32 v77, v77
	v_rcp_f32_e32 v78, v78
	v_rcp_f32_e32 v79, v79
	v_rcp_f32_e32 v72, v72
	v_rcp_f32_e32 v73, v73
	v_rcp_f32_e32 v74, v74
	v_rcp_f32_e32 v75, v75
	v_add_u32_e32 v242, 48, v150
	v_mad_i64_i32 v[240:241], s[8:9], v242, s72, v[212:213]
	v_pk_mul_f32 v[68:69], v[68:69], v[76:77]
	v_pk_mul_f32 v[70:71], v[70:71], v[78:79]
	v_pk_mul_f32 v[64:65], v[64:65], v[72:73]
	v_pk_mul_f32 v[66:67], v[66:67], v[74:75]
	v_lshl_add_u64 v[240:241], v[240:241], 0, v[214:215]
	v_cvt_pk_bf16_f32 v244, v68, v69
	v_cvt_pk_bf16_f32 v245, v70, v71
	v_cvt_pk_bf16_f32 v246, v64, v65
	v_cvt_pk_bf16_f32 v247, v66, v67
	global_store_dwordx4 v[240:241], v[244:247], off sc1
	s_nop 1
	v_mul_f32_e32 v238, 0xbfb8aa3b, v186
	v_pk_mul_f32 v[52:53], v[60:61], v[52:53]
	v_pk_mul_f32 v[54:55], v[62:63], v[54:55]
	v_pk_mul_f32 v[48:49], v[56:57], v[48:49]
	v_pk_mul_f32 v[50:51], v[58:59], v[50:51]
	v_mul_f32_e32 v60, v238, v60
	v_mul_f32_e32 v61, v238, v61
	v_mul_f32_e32 v62, v238, v62
	v_mul_f32_e32 v63, v238, v63
	v_mul_f32_e32 v56, v238, v56
	v_mul_f32_e32 v57, v238, v57
	v_mul_f32_e32 v58, v238, v58
	v_mul_f32_e32 v59, v238, v59
	v_exp_f32_e32 v60, v60
	v_exp_f32_e32 v61, v61
	v_exp_f32_e32 v62, v62
	v_exp_f32_e32 v63, v63
	v_exp_f32_e32 v56, v56
	v_exp_f32_e32 v57, v57
	v_exp_f32_e32 v58, v58
	v_exp_f32_e32 v59, v59
	v_fma_f32 v60, v60, v188, v188
	v_fma_f32 v61, v61, v188, v188
	v_fma_f32 v62, v62, v188, v188
	v_fma_f32 v63, v63, v188, v188
	v_fma_f32 v56, v56, v188, v188
	v_fma_f32 v57, v57, v188, v188
	v_fma_f32 v58, v58, v188, v188
	v_fma_f32 v59, v59, v188, v188
	v_rcp_f32_e32 v60, v60
	v_rcp_f32_e32 v61, v61
	v_rcp_f32_e32 v62, v62
	v_rcp_f32_e32 v63, v63
	v_rcp_f32_e32 v56, v56
	v_rcp_f32_e32 v57, v57
	v_rcp_f32_e32 v58, v58
	v_rcp_f32_e32 v59, v59
	v_add_u32_e32 v242, 0x80, v150
	v_mad_i64_i32 v[240:241], s[8:9], v242, s72, v[212:213]
	v_pk_mul_f32 v[52:53], v[52:53], v[60:61]
	v_pk_mul_f32 v[54:55], v[54:55], v[62:63]
	v_pk_mul_f32 v[48:49], v[48:49], v[56:57]
	v_pk_mul_f32 v[50:51], v[50:51], v[58:59]
	v_lshl_add_u64 v[240:241], v[240:241], 0, v[214:215]
	v_cvt_pk_bf16_f32 v244, v52, v53
	v_cvt_pk_bf16_f32 v245, v54, v55
	v_cvt_pk_bf16_f32 v246, v48, v49
	v_cvt_pk_bf16_f32 v247, v50, v51
	global_store_dwordx4 v[240:241], v[244:247], off sc1
	s_nop 1
	v_mul_f32_e32 v238, 0xbfb8aa3b, v200
	v_pk_mul_f32 v[36:37], v[44:45], v[36:37]
	v_pk_mul_f32 v[38:39], v[46:47], v[38:39]
	v_pk_mul_f32 v[32:33], v[40:41], v[32:33]
	v_pk_mul_f32 v[34:35], v[42:43], v[34:35]
	v_mul_f32_e32 v44, v238, v44
	v_mul_f32_e32 v45, v238, v45
	v_mul_f32_e32 v46, v238, v46
	v_mul_f32_e32 v47, v238, v47
	v_mul_f32_e32 v40, v238, v40
	v_mul_f32_e32 v41, v238, v41
	v_mul_f32_e32 v42, v238, v42
	v_mul_f32_e32 v43, v238, v43
	v_exp_f32_e32 v44, v44
	v_exp_f32_e32 v45, v45
	v_exp_f32_e32 v46, v46
	v_exp_f32_e32 v47, v47
	v_exp_f32_e32 v40, v40
	v_exp_f32_e32 v41, v41
	v_exp_f32_e32 v42, v42
	v_exp_f32_e32 v43, v43
	v_fma_f32 v44, v44, v202, v202
	v_fma_f32 v45, v45, v202, v202
	v_fma_f32 v46, v46, v202, v202
	v_fma_f32 v47, v47, v202, v202
	v_fma_f32 v40, v40, v202, v202
	v_fma_f32 v41, v41, v202, v202
	v_fma_f32 v42, v42, v202, v202
	v_fma_f32 v43, v43, v202, v202
	v_rcp_f32_e32 v44, v44
	v_rcp_f32_e32 v45, v45
	v_rcp_f32_e32 v46, v46
	v_rcp_f32_e32 v47, v47
	v_rcp_f32_e32 v40, v40
	v_rcp_f32_e32 v41, v41
	v_rcp_f32_e32 v42, v42
	v_rcp_f32_e32 v43, v43
	v_add_u32_e32 v242, 0x90, v150
	v_mad_i64_i32 v[240:241], s[8:9], v242, s72, v[212:213]
	v_pk_mul_f32 v[36:37], v[36:37], v[44:45]
	v_pk_mul_f32 v[38:39], v[38:39], v[46:47]
	v_pk_mul_f32 v[32:33], v[32:33], v[40:41]
	v_pk_mul_f32 v[34:35], v[34:35], v[42:43]
	v_lshl_add_u64 v[240:241], v[240:241], 0, v[214:215]
	v_cvt_pk_bf16_f32 v244, v36, v37
	v_cvt_pk_bf16_f32 v245, v38, v39
	v_cvt_pk_bf16_f32 v246, v32, v33
	v_cvt_pk_bf16_f32 v247, v34, v35
	global_store_dwordx4 v[240:241], v[244:247], off sc1
	s_nop 1
	v_mul_f32_e32 v238, 0xbfb8aa3b, v204
	v_pk_mul_f32 v[20:21], v[28:29], v[20:21]
	v_pk_mul_f32 v[22:23], v[30:31], v[22:23]
	v_pk_mul_f32 v[16:17], v[24:25], v[16:17]
	v_pk_mul_f32 v[18:19], v[26:27], v[18:19]
	v_mul_f32_e32 v28, v238, v28
	v_mul_f32_e32 v29, v238, v29
	v_mul_f32_e32 v30, v238, v30
	v_mul_f32_e32 v31, v238, v31
	v_mul_f32_e32 v24, v238, v24
	v_mul_f32_e32 v25, v238, v25
	v_mul_f32_e32 v26, v238, v26
	v_mul_f32_e32 v27, v238, v27
	v_exp_f32_e32 v28, v28
	v_exp_f32_e32 v29, v29
	v_exp_f32_e32 v30, v30
	v_exp_f32_e32 v31, v31
	v_exp_f32_e32 v24, v24
	v_exp_f32_e32 v25, v25
	v_exp_f32_e32 v26, v26
	v_exp_f32_e32 v27, v27
	v_fma_f32 v28, v28, v206, v206
	v_fma_f32 v29, v29, v206, v206
	v_fma_f32 v30, v30, v206, v206
	v_fma_f32 v31, v31, v206, v206
	v_fma_f32 v24, v24, v206, v206
	v_fma_f32 v25, v25, v206, v206
	v_fma_f32 v26, v26, v206, v206
	v_fma_f32 v27, v27, v206, v206
	v_rcp_f32_e32 v28, v28
	v_rcp_f32_e32 v29, v29
	v_rcp_f32_e32 v30, v30
	v_rcp_f32_e32 v31, v31
	v_rcp_f32_e32 v24, v24
	v_rcp_f32_e32 v25, v25
	v_rcp_f32_e32 v26, v26
	v_rcp_f32_e32 v27, v27
	v_add_u32_e32 v242, 0xa0, v150
	v_mad_i64_i32 v[240:241], s[8:9], v242, s72, v[212:213]
	v_pk_mul_f32 v[20:21], v[20:21], v[28:29]
	v_pk_mul_f32 v[22:23], v[22:23], v[30:31]
	v_pk_mul_f32 v[16:17], v[16:17], v[24:25]
	v_pk_mul_f32 v[18:19], v[18:19], v[26:27]
	v_lshl_add_u64 v[240:241], v[240:241], 0, v[214:215]
	v_cvt_pk_bf16_f32 v244, v20, v21
	v_cvt_pk_bf16_f32 v245, v22, v23
	v_cvt_pk_bf16_f32 v246, v16, v17
	v_cvt_pk_bf16_f32 v247, v18, v19
	global_store_dwordx4 v[240:241], v[244:247], off sc1
	s_nop 1
	v_mul_f32_e32 v238, 0xbfb8aa3b, v208
	v_pk_mul_f32 v[4:5], v[12:13], v[4:5]
	v_pk_mul_f32 v[6:7], v[14:15], v[6:7]
	v_pk_mul_f32 v[0:1], v[8:9], v[0:1]
	v_pk_mul_f32 v[2:3], v[10:11], v[2:3]
	v_mul_f32_e32 v12, v238, v12
	v_mul_f32_e32 v13, v238, v13
	v_mul_f32_e32 v14, v238, v14
	v_mul_f32_e32 v15, v238, v15
	v_mul_f32_e32 v8, v238, v8
	v_mul_f32_e32 v9, v238, v9
	v_mul_f32_e32 v10, v238, v10
	v_mul_f32_e32 v11, v238, v11
	v_exp_f32_e32 v12, v12
	v_exp_f32_e32 v13, v13
	v_exp_f32_e32 v14, v14
	v_exp_f32_e32 v15, v15
	v_exp_f32_e32 v8, v8
	v_exp_f32_e32 v9, v9
	v_exp_f32_e32 v10, v10
	v_exp_f32_e32 v11, v11
	v_fma_f32 v12, v12, v210, v210
	v_fma_f32 v13, v13, v210, v210
	v_fma_f32 v14, v14, v210, v210
	v_fma_f32 v15, v15, v210, v210
	v_fma_f32 v8, v8, v210, v210
	v_fma_f32 v9, v9, v210, v210
	v_fma_f32 v10, v10, v210, v210
	v_fma_f32 v11, v11, v210, v210
	v_rcp_f32_e32 v12, v12
	v_rcp_f32_e32 v13, v13
	v_rcp_f32_e32 v14, v14
	v_rcp_f32_e32 v15, v15
	v_rcp_f32_e32 v8, v8
	v_rcp_f32_e32 v9, v9
	v_rcp_f32_e32 v10, v10
	v_rcp_f32_e32 v11, v11
	v_add_u32_e32 v242, 0xb0, v150
	v_mad_i64_i32 v[240:241], s[8:9], v242, s72, v[212:213]
	v_pk_mul_f32 v[4:5], v[4:5], v[12:13]
	v_pk_mul_f32 v[6:7], v[6:7], v[14:15]
	v_pk_mul_f32 v[0:1], v[0:1], v[8:9]
	v_pk_mul_f32 v[2:3], v[2:3], v[10:11]
	v_lshl_add_u64 v[240:241], v[240:241], 0, v[214:215]
	v_cvt_pk_bf16_f32 v244, v4, v5
	v_cvt_pk_bf16_f32 v245, v6, v7
	v_cvt_pk_bf16_f32 v246, v0, v1
	v_cvt_pk_bf16_f32 v247, v2, v3
	global_store_dwordx4 v[240:241], v[244:247], off sc1
	s_andn2_b64 vcc, exec, s[38:39]
	s_mov_b64 s[8:9], -1
	s_cbranch_vccnz .LBB0_474
